# static s_setprio 3 for waves 0-3 restricted to the K=1024 GEMM phases (in-proj, merge gates, out-proj); up-merge phase at priority 0
# speedup vs baseline: 1.0036x; 1.0036x over previous
.LBB0_24:
	s_mov_b32 s72, s34
	v_readlane_b32 s20, v254, 0
	s_cmp_lg_u32 s70, 0
	s_mov_b64 s[2:3], -1
	s_cbranch_scc0 .LBB0_477
	s_add_i32 s2, s70, -1
	s_mul_hi_i32 s3, s2, 0x92492493
	s_add_i32 s3, s3, s2
	s_lshr_b32 s4, s3, 31
	s_ashr_i32 s3, s3, 2
	s_add_i32 s24, s3, s4
	s_mul_i32 s3, s24, 7
	s_sub_i32 s11, s2, s3
	s_setprio 0
	s_cmp_eq_u32 s11, 0
	s_cbranch_scc1 .Lsp_gemm
	s_cmp_lt_u32 s11, 4
	s_cbranch_scc1 .Lsp_done
	s_cmp_eq_u32 s11, 5
	s_cbranch_scc1 .Lsp_done
